# v12 + attn2 V^T LDS tile pitch 144 / permuted 16-key groups: PV operands via ds_read_b128 instead of ds_read2_b64
# baseline (speedup 1.0000x reference)
;     ...
;         f32x16 o[DVB];
; #pragma unroll
;         for (int db = 0; db < DVB; ++db)
; #pragma unroll
;             for (int i = 0; i < 16; ++i) o[db][i] = 0.f;
;         float m = -1e30f, l = 0.f;
;         constexpr bool DEEP = (MODE != 0);
;         u32x4 rgE[NJ], rgO[NJ]; float ckrE = 0.f, ckrO = 0.f;
;         auto gload = [&](u32x4 (&rg)[NJ], float& ckr, int t) {
; #pragma unroll
;             for (int j = 0; j < NJ; ++j) rg[j] = *(const u32x4*)(src[j] + (size_t)t * step[j]);
;             if (MODE == 1 && tid < 64) ckr = ckp[t * 64 + tid];
;         };
;         auto lstore = [&](const u32x4 (&rg)[NJ], const float ckr, int stg) {
;             unsigned char* sb = lds + stg * STG;
; #pragma unroll
;             for (int j = 0; j < NJ; ++j) {
;                 if (j < NKJ) *(u32x4*)(sb + j * 9216 + lrow * 144 + lkc * 16) = rg[j];
;                 else { unsigned char* d = sb + VT_OFF + (lrow + 64 * (j - NKJ)) * 136 + lkc * 16; u32x2 a, c; a.x = rg[j].x; a.y = rg[j].y; c.x = rg[j].z; c.y = rg[j].w; *(u32x2*)d = a; *(u32x2*)(d + 8) = c; }
;             }
;             if (MODE == 1 && tid < 64) *(float*)(sb + CK_OFF + tid * 4) = ckr;
;         };
;         const unsigned koff = cmap * 9216 + r32 * 144 + hh * 16;
;         const unsigned voff = VT_OFF + r32 * 136 + hh * 8;
.LBB0_3589:
	s_or_b64 exec, exec, s[2:3]
	v_cmp_gt_i32_e32 vcc, 11, v1
	v_cmp_lt_i32_e64 s[2:3], 10, v5
	s_and_b64 s[0:1], vcc, s[2:3]
	s_and_saveexec_b64 s[8:9], s[0:1]
	s_cbranch_execz .LBB0_3644
	s_add_u32 s10, s42, 0x7200000
	s_addc_u32 s11, s43, 0
	s_add_u32 s12, s42, 0x19200000
	s_addc_u32 s13, s43, 0
	v_and_b32_e32 v1, 7, v0
	s_add_u32 s14, s42, 0x1d200000
	v_mov_b32_e32 v3, 0
	s_addc_u32 s15, s43, 0
	s_not_b32 s0, s33
	v_lshlrev_b32_e32 v166, 4, v1
	v_mov_b32_e32 v167, v3
	s_add_i32 s28, s86, s0
	v_lshl_add_u64 v[4:5], s[42:43], 0, v[166:167]
	s_mov_b64 s[0:1], 0x15200000
	v_lshrrev_b32_e32 v2, 1, v0
	v_lshl_add_u64 v[168:169], v[4:5], 0, s[0:1]
	s_movk_i32 s1, 0x90
	v_and_b32_e32 v195, 0xe0, v2
	v_mad_u32_u24 v35, v171, s1, 0
	v_and_b32_e32 v2, 0x1f8, v0
	v_and_b32_e32 v211, 1, v0
	v_lshlrev_b32_e32 v211, 3, v211
	v_sub_u32_e32 v198, v35, v211
	v_mov_b32_e32 v2, 0x3f80
	v_cmp_eq_u32_e64 s[2:3], 0, v107
	v_lshlrev_b32_e32 v34, 3, v1
	v_mul_u32_u24_e32 v1, 0x90, v194
	v_cndmask_b32_e64 v130, 0, v2, s[2:3]
	v_mov_b32_e32 v2, 0xd800
	v_add_u32_e32 v36, 0, v84
	v_mad_u32_u24 v201, v171, s1, v2
	v_mad_u32_u24 v2, v194, s1, v84
	v_mov_b32_e32 v4, 0x9000
	v_mov_b32_e32 v18, v3
	v_mov_b32_e32 v19, v3
	v_mov_b32_e32 v20, v3
	v_mov_b32_e32 v21, v3
	v_mov_b32_e32 v22, v3
	v_mov_b32_e32 v23, v3
	v_mov_b32_e32 v24, v3
	v_mov_b32_e32 v25, v3
	v_mov_b32_e32 v26, v3
	v_mov_b32_e32 v27, v3
	v_mov_b32_e32 v28, v3
	v_mov_b32_e32 v29, v3
	v_mov_b32_e32 v30, v3
	v_mov_b32_e32 v31, v3
	v_mov_b32_e32 v32, v3
	v_mov_b32_e32 v33, v3
	v_add_u32_e32 v202, 0x4800, v2
	v_mad_u32_u24 v203, v171, s1, v4
	v_add_u32_e32 v204, 0x9000, v2
	v_mov_b32_e32 v2, v3
	v_mov_b32_e32 v4, v3
	v_mov_b32_e32 v5, v3
	v_mov_b32_e32 v6, v3
	v_mov_b32_e32 v7, v3
	v_mov_b32_e32 v8, v3
	v_mov_b32_e32 v9, v3
	v_mov_b32_e32 v10, v3
	v_mov_b32_e32 v11, v3
	v_mov_b32_e32 v12, v3
	v_mov_b32_e32 v13, v3
	v_mov_b32_e32 v14, v3
	v_mov_b32_e32 v15, v3
	v_mov_b32_e32 v16, v3
	v_mov_b32_e32 v17, v3
	v_lshlrev_b32_e32 v174, 1, v34
	v_add_u32_e32 v205, v35, v166
	s_movk_i32 s1, 0x6c00
	v_add_u32_e32 v207, v36, v1
	v_mov_b64_e32 v[48:49], v[32:33]
	v_mul_u32_u24_e32 v196, 0x90, v194
	s_mov_b32 s0, 0
	v_mov_b32_e32 v197, v198
	v_mov_b32_e32 v131, v3
	v_mov_b32_e32 v132, v3
	v_mov_b32_e32 v133, v3
	v_lshlrev_b32_e32 v170, 2, v107
	v_add_u32_e32 v199, 0, v84
	v_add_u32_e32 v200, 0, v166
	s_movk_i32 s29, 0x1c00
	v_lshlrev_b32_e32 v172, 1, v82
	s_mov_b64 s[16:17], 0x800
	s_movk_i32 s30, 0x2400
	v_add3_u32 v206, v198, v166, s1
	s_mov_b32 s31, 0xefa18f08
	s_mov_b32 s34, 0xff800000
	v_mov_b32_e32 v177, 0x41000000
	s_mov_b32 s35, 0xb400
	s_mov_b32 s36, 0xfc00
	s_mov_b64 s[18:19], 0x100
	s_mov_b64 s[20:21], 0xe0000
	s_mov_b32 s37, 0
	v_mov_b64_e32 v[46:47], v[30:31]
	v_mov_b64_e32 v[44:45], v[28:29]
	v_mov_b64_e32 v[42:43], v[26:27]
	v_mov_b64_e32 v[40:41], v[24:25]
	v_mov_b64_e32 v[38:39], v[22:23]
	v_mov_b64_e32 v[36:37], v[20:21]
	v_mov_b64_e32 v[34:35], v[18:19]
	v_mov_b64_e32 v[32:33], v[16:17]
	v_mov_b64_e32 v[30:31], v[14:15]
	v_mov_b64_e32 v[28:29], v[12:13]
	v_mov_b64_e32 v[26:27], v[10:11]
	v_mov_b64_e32 v[24:25], v[8:9]
	v_mov_b64_e32 v[22:23], v[6:7]
	v_mov_b64_e32 v[20:21], v[4:5]
	v_mov_b64_e32 v[18:19], v[2:3]
	s_branch .LBB0_3594

;     ...
;             src[0] = P + (size_t)(b * SEQ + lrow) * PITCH + 1024 + h * 64 + lkc * 8; step[0] = (size_t)64 * PITCH;
;             src[1] = VT + (size_t)(b * 1024 + h * 64 + lrow) * SEQ + lkc * 8; step[1] = 64;
;         }
;         const int qcol = (MODE == 0) ? (h * 2 + cmap) * 64 : (MODE == 1 ? 1536 + h * 64 : h * 64);
;         bf16x8 qf[4];
; #pragma unroll
;         for (int ks = 0; ks < 4; ++ks) qf[ks] = *(const bf16x8*)(P + (size_t)(b * SEQ + myq) * PITCH + qcol + 16 * ks + 8 * hh);
;     ...
;         auto gload = [&](u32x4 (&rg)[NJ], float& ckr, int t) {
; #pragma unroll
;             for (int j = 0; j < NJ; ++j) rg[j] = *(const u32x4*)(src[j] + (size_t)t * step[j]);
;             if (MODE == 1 && tid < 64) ckr = ckp[t * 64 + tid];
;         };
;         auto lstore = [&](const u32x4 (&rg)[NJ], const float ckr, int stg) {
;             unsigned char* sb = lds + stg * STG;
; #pragma unroll
;             for (int j = 0; j < NJ; ++j) {
;                 if (j < NKJ) *(u32x4*)(sb + j * 9216 + lrow * 144 + lkc * 16) = rg[j];
;                 else { unsigned char* d = sb + VT_OFF + (lrow + 64 * (j - NKJ)) * 136 + lkc * 16; u32x2 a, c; a.x = rg[j].x; a.y = rg[j].y; c.x = rg[j].z; c.y = rg[j].w; *(u32x2*)d = a; *(u32x2*)(d + 8) = c; }
.LBB0_3597:
	s_ashr_i32 s0, s39, 31
	s_lshr_b32 s0, s0, 28
	s_add_i32 s0, s39, s0
	s_ashr_i32 s4, s0, 4
	s_and_b32 s0, s0, 0x3fffff0
	s_sub_i32 s5, s39, s0
	s_lshl_b32 s7, s4, 13
	s_lshl_b32 s6, s38, 8
	v_or_b32_e32 v1, s7, v171
	v_mov_b64_e32 v[4:5], s[10:11]
	s_lshl_b32 s22, s5, 6
	v_or_b32_e32 v208, s6, v195
	v_mad_i64_i32 v[6:7], s[0:1], v1, s29, v[4:5]
	s_ashr_i32 s23, s22, 31
	s_lshl_b32 s4, s4, 10
	v_or_b32_e32 v2, s7, v194
	s_lshl_b64 s[0:1], s[22:23], 1
	s_add_i32 s4, s4, s22
	v_add_u32_e32 v178, v2, v208
	v_lshl_add_u64 v[8:9], v[6:7], 0, s[0:1]
	v_add_u32_e32 v6, s4, v171
	v_mad_i64_i32 v[4:5], s[4:5], v178, s29, v[4:5]
	v_lshl_add_u64 v[4:5], v[4:5], 0, s[0:1]
	v_mov_b32_e32 v173, v3
	v_lshl_add_u64 v[10:11], v[4:5], 0, v[172:173]
	v_ashrrev_i32_e32 v7, 31, v6
	v_ashrrev_i32_e32 v179, 31, v178
	global_load_dwordx4 v[142:145], v[10:11], off
	global_load_dwordx4 v[146:149], v[10:11], off offset:32
	v_mov_b32_e32 v175, v3
	v_lshlrev_b64 v[6:7], 14, v[6:7]
	v_lshl_add_u64 v[12:13], v[8:9], 0, v[174:175]
	v_lshlrev_b64 v[180:181], 10, v[178:179]
	v_lshl_add_u64 v[4:5], s[14:15], 0, v[180:181]
	v_lshl_add_u64 v[8:9], v[168:169], 0, v[6:7]
	global_load_dwordx4 v[158:161], v[12:13], off offset:2048
	global_load_dwordx2 v[116:117], v[4:5], off
	global_load_dwordx4 v[162:165], v[8:9], off
	global_load_dwordx4 v[150:153], v[10:11], off offset:64
	global_load_dwordx4 v[154:157], v[10:11], off offset:96
	s_addk_i32 s6, 0x100
	s_ashr_i32 s40, s6, 6
	s_cmp_gt_i32 s40, 1
	v_add3_u32 v2, v198, v166, s30
	s_cselect_b64 s[4:5], -1, 0
	v_lshl_add_u64 v[10:11], v[12:13], 0, s[16:17]
	s_cmp_lt_i32 s40, 2
	s_waitcnt vmcnt(0)
	ds_write_b128 v205, v[158:161]
	ds_write2_b64 v2, v[162:163], v[164:165] offset1:2
	s_cbranch_scc0 .LBB0_3641
	s_cmp_lt_i32 s40, 3
	s_cbranch_scc0 .LBB0_3642

; #define MFMA32(a, b, c) __builtin_amdgcn_mfma_f32_32x32x16_bf16((a), (b), (c), 0, 0, 0)
; DI unsigned pk_bf16(float a, float b) { f32x2 v = {a, b}; bf2_t r = __builtin_convertvector(v, bf2_t); return __builtin_bit_cast(unsigned, r); }
;     ...
;         auto lstore = [&](const u32x4 (&rg)[NJ], const float ckr, int stg) {
;             unsigned char* sb = lds + stg * STG;
; #pragma unroll
;             for (int j = 0; j < NJ; ++j) {
;                 if (j < NKJ) *(u32x4*)(sb + j * 9216 + lrow * 144 + lkc * 16) = rg[j];
;                 else { unsigned char* d = sb + VT_OFF + (lrow + 64 * (j - NKJ)) * 136 + lkc * 16; u32x2 a, c; a.x = rg[j].x; a.y = rg[j].y; c.x = rg[j].z; c.y = rg[j].w; *(u32x2*)d = a; *(u32x2*)(d + 8) = c; }
;     ...
;             float ls = 0.f;
; #pragma unroll
;             for (int blk = 0; blk < 2; ++blk)
; #pragma unroll
;                 for (int i = 0; i < 16; ++i) { const float e = __builtin_amdgcn_exp2f(s[blk][i]); s[blk][i] = e; ls += e; }
;             l += ls;
;             }
; #pragma unroll
;             for (int blk = 0; blk < 2; ++blk)
; #pragma unroll
;                 for (int sp = 0; sp < 2; ++sp) {
;                     u32x4 pw;
;                     pw.x = pk_bf16(s[blk][8 * sp + 0], s[blk][8 * sp + 1]); pw.y = pk_bf16(s[blk][8 * sp + 2], s[blk][8 * sp + 3]);
;                     pw.z = pk_bf16(s[blk][8 * sp + 4], s[blk][8 * sp + 5]); pw.w = pk_bf16(s[blk][8 * sp + 6], s[blk][8 * sp + 7]);
;                     const bf16x8 pf = __builtin_bit_cast(bf16x8, pw);
; #pragma unroll
;                     for (int db = 0; db < DVB; ++db) {
;                         const unsigned char* va = sb + voff + db * 32 * 136 + (32 * blk + 16 * sp) * 2;
;                         const u32x2 lo = *(const u32x2*)va, hi = *(const u32x2*)(va + 16);
;                         u32x4 vw; vw.x = lo.x; vw.y = lo.y; vw.z = hi.x; vw.w = hi.y;
;                         o[db] = MFMA32(__builtin_bit_cast(bf16x8, vw), pf, o[db]);
;                     }
;                 }
.LBB0_3617:
	s_mul_hi_u32 s0, s49, 0xaaaaaaab
	s_lshr_b32 s0, s0, 1
	s_mul_i32 s0, s0, 0xd800
	v_exp_f32_e32 v35, v1
	v_subrev_u32_e32 v1, s0, v196
	v_add3_u32 v1, v199, s48, v1
	v_exp_f32_e32 v34, v2
	v_add_u32_e32 v2, 0x2000, v1
	ds_read_b128 v[44:47], v2 offset:1024
	v_exp_f32_e32 v18, v18
	v_exp_f32_e32 v19, v19
	v_exp_f32_e32 v20, v20
	v_exp_f32_e32 v21, v21
	v_exp_f32_e32 v22, v22
	v_exp_f32_e32 v23, v23
	v_exp_f32_e32 v24, v24
	v_exp_f32_e32 v25, v25
	v_cvt_pk_bf16_f32 v40, v18, v19
	v_cvt_pk_bf16_f32 v41, v20, v21
	v_cvt_pk_bf16_f32 v42, v22, v23
	v_cvt_pk_bf16_f32 v43, v24, v25
	v_add_u32_e32 v1, 0x3000, v1
	v_exp_f32_e32 v36, v4
	s_waitcnt lgkmcnt(0)
	v_mfma_f32_32x32x16_bf16 v[98:113], v[44:47], v[40:43], v[98:113]
	ds_read_b128 v[44:47], v1 offset:1536
	v_add_f32_e32 v4, 0, v18
	v_add_f32_e32 v4, v19, v4
	v_add_f32_e32 v4, v20, v4
	v_add_f32_e32 v4, v21, v4
	v_exp_f32_e32 v26, v26
	v_add_f32_e32 v4, v22, v4
	v_exp_f32_e32 v27, v27
	v_add_f32_e32 v4, v23, v4
	v_exp_f32_e32 v28, v28
	v_add_f32_e32 v4, v24, v4
	v_exp_f32_e32 v29, v29
	v_add_f32_e32 v4, v25, v4
	v_exp_f32_e32 v30, v30
	v_add_f32_e32 v4, v26, v4
	v_exp_f32_e32 v31, v31
	s_waitcnt lgkmcnt(0)
	v_mfma_f32_32x32x16_bf16 v[82:97], v[44:47], v[40:43], v[82:97]
	v_add_f32_e32 v4, v27, v4
	ds_read_b128 v[40:43], v2 offset:1056
	v_exp_f32_e32 v32, v32
	v_add_f32_e32 v4, v28, v4
	v_exp_f32_e32 v33, v33
	v_add_f32_e32 v4, v29, v4
	v_add_f32_e32 v4, v30, v4
	v_add_f32_e32 v4, v31, v4
	v_add_f32_e32 v4, v32, v4
	v_exp_f32_e32 v37, v17
	v_add_f32_e32 v4, v33, v4
	v_exp_f32_e32 v38, v16
	v_add_f32_e32 v4, v34, v4
	v_add_f32_e32 v4, v35, v4
	v_exp_f32_e32 v39, v5
	v_cvt_pk_bf16_f32 v44, v26, v27
	v_cvt_pk_bf16_f32 v45, v28, v29
	v_cvt_pk_bf16_f32 v46, v30, v31
	v_cvt_pk_bf16_f32 v47, v32, v33
	ds_read_b128 v[114:117], v1 offset:1568
	v_add_f32_e32 v4, v36, v4
	s_waitcnt lgkmcnt(1)
	v_mfma_f32_32x32x16_bf16 v[98:113], v[40:43], v[44:47], v[98:113]
	v_exp_f32_e32 v40, v6
	v_add_f32_e32 v4, v37, v4
	v_exp_f32_e32 v41, v7
	v_add_f32_e32 v4, v38, v4
	v_add_f32_e32 v4, v39, v4
	v_add_f32_e32 v4, v40, v4
	v_add_f32_e32 v16, v41, v4
	ds_read_b128 v[4:7], v2 offset:1088
	ds_read_b128 v[118:121], v1 offset:1600
	s_waitcnt lgkmcnt(2)
	v_mfma_f32_32x32x16_bf16 v[82:97], v[114:117], v[44:47], v[82:97]
	v_exp_f32_e32 v42, v8
	v_exp_f32_e32 v43, v9
	v_cvt_pk_bf16_f32 v114, v34, v35
	v_cvt_pk_bf16_f32 v115, v36, v37
	v_cvt_pk_bf16_f32 v116, v38, v39
	v_cvt_pk_bf16_f32 v117, v40, v41
	v_exp_f32_e32 v46, v12
	v_exp_f32_e32 v47, v13
	s_waitcnt lgkmcnt(1)
	v_mfma_f32_32x32x16_bf16 v[98:113], v[4:7], v[114:117], v[98:113]
	v_add_f32_e32 v4, v42, v16
	v_add_f32_e32 v16, v43, v4
	ds_read_b128 v[4:7], v2 offset:1120
	v_exp_f32_e32 v48, v14
	v_exp_f32_e32 v49, v15
	ds_read_b128 v[12:15], v1 offset:1632
	v_exp_f32_e32 v44, v10
	s_waitcnt lgkmcnt(2)
	v_mfma_f32_32x32x16_bf16 v[82:97], v[118:121], v[114:117], v[82:97]
	v_exp_f32_e32 v45, v11
	v_cvt_pk_bf16_f32 v8, v42, v43
	v_cvt_pk_bf16_f32 v10, v46, v47
	v_cvt_pk_bf16_f32 v11, v48, v49
	v_cvt_pk_bf16_f32 v9, v44, v45
	v_add_f32_e32 v1, v44, v16
	v_add_f32_e32 v1, v45, v1
	s_waitcnt lgkmcnt(1)
	v_mfma_f32_32x32x16_bf16 v[98:113], v[4:7], v[8:11], v[98:113]
	v_add_f32_e32 v1, v46, v1
	v_add_f32_e32 v1, v47, v1
	v_add_f32_e32 v1, v48, v1
	v_add_f32_e32 v1, v49, v1
	v_add_f32_e32 v173, v173, v1
	s_waitcnt lgkmcnt(0)
	v_mfma_f32_32x32x16_bf16 v[82:97], v[12:15], v[8:11], v[82:97]
.LBB0_3618:
	s_or_b64 exec, exec, s[26:27]
	s_mul_hi_u32 s0, s47, 0xaaaaaaab
	s_lshr_b32 s0, s0, 1
	s_andn2_b64 vcc, exec, s[24:25]
	s_mul_i32 s0, s0, 0xd800
	s_cbranch_vccnz .LBB0_3620
	v_subrev_u32_e32 v1, s0, v203
	v_add_u32_e32 v4, s48, v200
	v_subrev_u32_e32 v2, s0, v197
	v_add_u32_e32 v1, v4, v1
	s_waitcnt vmcnt(1)
	ds_write_b128 v1, v[134:137]
	v_add3_u32 v1, v4, v2, s35
	s_waitcnt vmcnt(0)
	ds_write2_b64 v1, v[138:139], v[140:141] offset1:2

; #define MFMA32(a, b, c) __builtin_amdgcn_mfma_f32_32x32x16_bf16((a), (b), (c), 0, 0, 0)
; DI unsigned pk_bf16(float a, float b) { f32x2 v = {a, b}; bf2_t r = __builtin_convertvector(v, bf2_t); return __builtin_bit_cast(unsigned, r); }
;     ...
;         auto lstore = [&](const u32x4 (&rg)[NJ], const float ckr, int stg) {
;             unsigned char* sb = lds + stg * STG;
; #pragma unroll
;             for (int j = 0; j < NJ; ++j) {
;                 if (j < NKJ) *(u32x4*)(sb + j * 9216 + lrow * 144 + lkc * 16) = rg[j];
;                 else { unsigned char* d = sb + VT_OFF + (lrow + 64 * (j - NKJ)) * 136 + lkc * 16; u32x2 a, c; a.x = rg[j].x; a.y = rg[j].y; c.x = rg[j].z; c.y = rg[j].w; *(u32x2*)d = a; *(u32x2*)(d + 8) = c; }
;     ...
;             float ls = 0.f;
; #pragma unroll
;             for (int blk = 0; blk < 2; ++blk)
; #pragma unroll
;                 for (int i = 0; i < 16; ++i) { const float e = __builtin_amdgcn_exp2f(s[blk][i]); s[blk][i] = e; ls += e; }
;             l += ls;
;             }
; #pragma unroll
;             for (int blk = 0; blk < 2; ++blk)
; #pragma unroll
;                 for (int sp = 0; sp < 2; ++sp) {
;                     u32x4 pw;
;                     pw.x = pk_bf16(s[blk][8 * sp + 0], s[blk][8 * sp + 1]); pw.y = pk_bf16(s[blk][8 * sp + 2], s[blk][8 * sp + 3]);
;                     pw.z = pk_bf16(s[blk][8 * sp + 4], s[blk][8 * sp + 5]); pw.w = pk_bf16(s[blk][8 * sp + 6], s[blk][8 * sp + 7]);
;                     const bf16x8 pf = __builtin_bit_cast(bf16x8, pw);
; #pragma unroll
;                     for (int db = 0; db < DVB; ++db) {
;                         const unsigned char* va = sb + voff + db * 32 * 136 + (32 * blk + 16 * sp) * 2;
;                         const u32x2 lo = *(const u32x2*)va, hi = *(const u32x2*)(va + 16);
;                         u32x4 vw; vw.x = lo.x; vw.y = lo.y; vw.z = hi.x; vw.w = hi.y;
;                         o[db] = MFMA32(__builtin_bit_cast(bf16x8, vw), pf, o[db]);
;                     }
;                 }
.LBB0_3635:
	v_exp_f32_e32 v51, v1
	v_subrev_u32_e32 v1, s51, v196
	v_add3_u32 v1, v199, s48, v1
	v_exp_f32_e32 v50, v2
	v_add_u32_e32 v2, 0x6800, v1
	ds_read_b128 v[76:79], v2 offset:1024
	v_exp_f32_e32 v52, v4
	v_exp_f32_e32 v53, v17
	v_exp_f32_e32 v54, v16
	v_exp_f32_e32 v55, v55
	v_exp_f32_e32 v56, v56
	v_exp_f32_e32 v57, v57
	v_cvt_pk_bf16_f32 v72, v50, v51
	v_cvt_pk_bf16_f32 v73, v52, v53
	v_cvt_pk_bf16_f32 v74, v54, v55
	v_cvt_pk_bf16_f32 v75, v56, v57
	v_add_u32_e32 v1, 0x7800, v1
	v_add_f32_e32 v4, 0, v50
	s_waitcnt lgkmcnt(0)
	v_mfma_f32_32x32x16_bf16 v[98:113], v[76:79], v[72:75], v[98:113]
	ds_read_b128 v[76:79], v1 offset:1536
	v_add_f32_e32 v4, v51, v4
	v_add_f32_e32 v4, v52, v4
	v_add_f32_e32 v4, v53, v4
	v_exp_f32_e32 v58, v58
	v_add_f32_e32 v4, v54, v4
	v_exp_f32_e32 v59, v59
	v_add_f32_e32 v4, v55, v4
	v_exp_f32_e32 v60, v60
	v_add_f32_e32 v4, v56, v4
	v_exp_f32_e32 v61, v61
	v_add_f32_e32 v4, v57, v4
	v_exp_f32_e32 v62, v62
	v_add_f32_e32 v4, v58, v4
	v_exp_f32_e32 v63, v63
	s_waitcnt lgkmcnt(0)
	v_mfma_f32_32x32x16_bf16 v[82:97], v[76:79], v[72:75], v[82:97]
	v_add_f32_e32 v4, v59, v4
	ds_read_b128 v[72:75], v2 offset:1056
	v_exp_f32_e32 v64, v64
	v_add_f32_e32 v4, v60, v4
	v_exp_f32_e32 v65, v65
	v_add_f32_e32 v4, v61, v4
	v_exp_f32_e32 v66, v66
	v_add_f32_e32 v4, v62, v4
	v_exp_f32_e32 v67, v67
	v_add_f32_e32 v4, v63, v4
	v_exp_f32_e32 v68, v68
	v_add_f32_e32 v4, v64, v4
	v_exp_f32_e32 v69, v69
	v_add_f32_e32 v4, v65, v4
	v_exp_f32_e32 v70, v70
	v_add_f32_e32 v4, v66, v4
	v_add_f32_e32 v4, v67, v4
	v_exp_f32_e32 v71, v5
	v_cvt_pk_bf16_f32 v76, v58, v59
	v_cvt_pk_bf16_f32 v77, v60, v61
	v_cvt_pk_bf16_f32 v78, v62, v63
	v_cvt_pk_bf16_f32 v79, v64, v65
	ds_read_b128 v[116:119], v1 offset:1568
	v_add_f32_e32 v4, v68, v4
	s_waitcnt lgkmcnt(1)
	v_mfma_f32_32x32x16_bf16 v[98:113], v[72:75], v[76:79], v[98:113]
	v_exp_f32_e32 v72, v6
	v_add_f32_e32 v4, v69, v4
	v_exp_f32_e32 v73, v7
	v_add_f32_e32 v4, v70, v4
	v_add_f32_e32 v4, v71, v4
	v_add_f32_e32 v4, v72, v4
	v_add_f32_e32 v16, v73, v4
	ds_read_b128 v[4:7], v2 offset:1088
	ds_read_b128 v[120:123], v1 offset:1600
	s_waitcnt lgkmcnt(2)
	v_mfma_f32_32x32x16_bf16 v[82:97], v[116:119], v[76:79], v[82:97]
	v_exp_f32_e32 v74, v8
	v_exp_f32_e32 v75, v9
	v_cvt_pk_bf16_f32 v116, v66, v67
	v_cvt_pk_bf16_f32 v117, v68, v69
	v_cvt_pk_bf16_f32 v118, v70, v71
	v_cvt_pk_bf16_f32 v119, v72, v73
	v_exp_f32_e32 v78, v12
	v_exp_f32_e32 v79, v13
	s_waitcnt lgkmcnt(1)
	v_mfma_f32_32x32x16_bf16 v[98:113], v[4:7], v[116:119], v[98:113]
	v_add_f32_e32 v4, v74, v16
	v_add_f32_e32 v16, v75, v4
	ds_read_b128 v[4:7], v2 offset:1120
	v_exp_f32_e32 v80, v14
	v_exp_f32_e32 v81, v15
	ds_read_b128 v[12:15], v1 offset:1632
	v_exp_f32_e32 v76, v10
	s_waitcnt lgkmcnt(2)
	v_mfma_f32_32x32x16_bf16 v[82:97], v[120:123], v[116:119], v[82:97]
	v_exp_f32_e32 v77, v11
	v_cvt_pk_bf16_f32 v8, v74, v75
	v_cvt_pk_bf16_f32 v10, v78, v79
	v_cvt_pk_bf16_f32 v11, v80, v81
	v_cvt_pk_bf16_f32 v9, v76, v77
	v_add_f32_e32 v1, v76, v16
	v_add_f32_e32 v1, v77, v1
	s_waitcnt lgkmcnt(1)
	v_mfma_f32_32x32x16_bf16 v[98:113], v[4:7], v[8:11], v[98:113]
	v_add_f32_e32 v1, v78, v1
	v_add_f32_e32 v1, v79, v1
	v_add_f32_e32 v1, v80, v1
	v_add_f32_e32 v1, v81, v1
	v_add_f32_e32 v173, v173, v1
	s_waitcnt lgkmcnt(0)
	v_mfma_f32_32x32x16_bf16 v[82:97], v[12:15], v[8:11], v[82:97]
.LBB0_3636:
	s_or_b64 exec, exec, s[24:25]
	s_and_b64 vcc, exec, s[4:5]
	s_cbranch_vccnz .LBB0_3638
	s_mul_hi_u32 s0, s46, 0xaaaaaaab
	s_lshr_b32 s0, s0, 1
	s_mul_i32 s0, s0, 0xd800
	v_subrev_u32_e32 v1, s0, v201
	v_add_u32_e32 v4, s48, v200
	v_subrev_u32_e32 v2, s0, v197
	v_add_u32_e32 v1, v4, v1
	ds_write_b128 v1, v[158:161]
	v_add3_u32 v1, v4, v2, s36
	ds_write2_b64 v1, v[162:163], v[164:165] offset1:2

;     ...
;         auto gload = [&](u32x4 (&rg)[NJ], float& ckr, int t) {
; #pragma unroll
;             for (int j = 0; j < NJ; ++j) rg[j] = *(const u32x4*)(src[j] + (size_t)t * step[j]);
;             if (MODE == 1 && tid < 64) ckr = ckp[t * 64 + tid];
;         };
;         auto lstore = [&](const u32x4 (&rg)[NJ], const float ckr, int stg) {
;             unsigned char* sb = lds + stg * STG;
; #pragma unroll
;             for (int j = 0; j < NJ; ++j) {
;                 if (j < NKJ) *(u32x4*)(sb + j * 9216 + lrow * 144 + lkc * 16) = rg[j];
;                 else { unsigned char* d = sb + VT_OFF + (lrow + 64 * (j - NKJ)) * 136 + lkc * 16; u32x2 a, c; a.x = rg[j].x; a.y = rg[j].y; c.x = rg[j].z; c.y = rg[j].w; *(u32x2*)d = a; *(u32x2*)(d + 8) = c; }
;     ...
;         if (ntl > 1) { gload(rgE, ckrE, j0 + 1); lstore(rgE, ckrE, 1); }
.LBB0_3641:
	v_add_co_u32_e32 v12, vcc, 0x70000, v10
	s_nop 1
	v_addc_co_u32_e32 v13, vcc, 0, v11, vcc
	global_load_dwordx4 v[158:161], v[12:13], off
	global_load_dwordx4 v[162:165], v[8:9], off offset:128
	s_waitcnt vmcnt(1)
	ds_write_b128 v205, v[158:161] offset:18432
	s_waitcnt vmcnt(0)
	ds_write2_b64 v206, v[162:163], v[164:165] offset1:2
	s_cmp_lt_i32 s40, 3
	s_cbranch_scc1 .LBB0_3599
